# nt cache hint also on the phase-0 weight transpose loads (each line read once) and the conv b-row load
# speedup vs baseline: 1.0099x; 1.0027x over previous
.LBB0_460:
	v_alignbit_b32 v16, v11, v10, 6
	v_and_b32_e32 v21, 0x1f8, v12
	v_and_b32_e32 v22, 0x1fff, v16
	v_lshlrev_b32_e32 v14, 1, v21
	v_mul_u32_u24_e32 v17, 0xc00, v16
	v_cmp_lt_u32_e64 s[98:99], 1, v22
	v_cmp_ne_u32_e64 s[100:101], 0, v22
	v_add_u32_e32 v17, v17, v14
	v_lshlrev_b32_e32 v23, 10, v16
	v_cndmask_b32_e64 v20, 0, v62, s[98:99]
	v_cndmask_b32_e64 v24, 0, v63, s[100:101]
	v_sub_u32_e32 v20, v17, v20
	v_sub_u32_e32 v24, v17, v24
	global_load_dwordx4 v[26:29], v20, s[28:29] offset:1024
	global_load_dwordx4 v[30:33], v20, s[28:29] offset:2048
	global_load_dwordx4 v[34:37], v24, s[28:29] offset:1024
	global_load_dwordx4 v[38:41], v24, s[28:29] offset:2048
	global_load_dwordx4 v[42:45], v17, s[28:29] offset:1024
	global_load_dwordx4 v[46:49], v17, s[28:29] offset:2048
	global_load_dwordx4 v[50:53], v17, s[28:29] nt
	v_add_u32_e32 v23, v23, v14
	v_mov_b32_e32 v2, v1
	v_mov_b32_e32 v3, v1
	v_mov_b32_e32 v4, v1
	v_mov_b32_e32 v5, v1
	v_mov_b32_e32 v6, v1
	v_mov_b32_e32 v7, v1
	v_mov_b32_e32 v8, v1
	v_mov_b32_e32 v9, v1
	s_waitcnt vmcnt(5)
	s_and_saveexec_b64 s[4:5], s[98:99]
	v_lshlrev_b32_e32 v54, 16, v26
	v_and_b32_e32 v55, 0xffff0000, v26
	v_lshlrev_b32_e32 v56, 16, v27
	v_and_b32_e32 v57, 0xffff0000, v27
	v_lshlrev_b32_e32 v58, 16, v28
	v_and_b32_e32 v59, 0xffff0000, v28
	v_lshlrev_b32_e32 v60, 16, v29
	v_and_b32_e32 v61, 0xffff0000, v29
	v_pk_mul_f32 v[88:89], v[64:65], v[54:55]
	v_pk_mul_f32 v[90:91], v[66:67], v[56:57]
	v_pk_mul_f32 v[92:93], v[68:69], v[58:59]
	v_pk_mul_f32 v[94:95], v[70:71], v[60:61]
	v_lshlrev_b32_e32 v54, 16, v30
	v_and_b32_e32 v55, 0xffff0000, v30
	v_lshlrev_b32_e32 v56, 16, v31
	v_and_b32_e32 v57, 0xffff0000, v31
	v_lshlrev_b32_e32 v58, 16, v32
	v_and_b32_e32 v59, 0xffff0000, v32
	v_lshlrev_b32_e32 v60, 16, v33
	v_and_b32_e32 v61, 0xffff0000, v33
	v_pk_fma_f32 v[2:3], v[88:89], v[54:55], v[2:3]
	v_pk_fma_f32 v[4:5], v[90:91], v[56:57], v[4:5]
	v_pk_fma_f32 v[6:7], v[92:93], v[58:59], v[6:7]
	v_pk_fma_f32 v[8:9], v[94:95], v[60:61], v[8:9]
	s_or_b64 exec, exec, s[4:5]
	s_waitcnt vmcnt(3)
	s_and_saveexec_b64 s[4:5], s[100:101]
	v_lshlrev_b32_e32 v54, 16, v34
	v_and_b32_e32 v55, 0xffff0000, v34
	v_lshlrev_b32_e32 v56, 16, v35
	v_and_b32_e32 v57, 0xffff0000, v35
	v_lshlrev_b32_e32 v58, 16, v36
	v_and_b32_e32 v59, 0xffff0000, v36
	v_lshlrev_b32_e32 v60, 16, v37
	v_and_b32_e32 v61, 0xffff0000, v37
	v_pk_mul_f32 v[88:89], v[72:73], v[54:55]
	v_pk_mul_f32 v[90:91], v[74:75], v[56:57]
	v_pk_mul_f32 v[92:93], v[76:77], v[58:59]
	v_pk_mul_f32 v[94:95], v[78:79], v[60:61]
	v_lshlrev_b32_e32 v54, 16, v38
	v_and_b32_e32 v55, 0xffff0000, v38
	v_lshlrev_b32_e32 v56, 16, v39
	v_and_b32_e32 v57, 0xffff0000, v39
	v_lshlrev_b32_e32 v58, 16, v40
	v_and_b32_e32 v59, 0xffff0000, v40
	v_lshlrev_b32_e32 v60, 16, v41
	v_and_b32_e32 v61, 0xffff0000, v41
	v_pk_fma_f32 v[2:3], v[88:89], v[54:55], v[2:3]
	v_pk_fma_f32 v[4:5], v[90:91], v[56:57], v[4:5]
	v_pk_fma_f32 v[6:7], v[92:93], v[58:59], v[6:7]
	v_pk_fma_f32 v[8:9], v[94:95], v[60:61], v[8:9]
	s_or_b64 exec, exec, s[4:5]
	s_waitcnt vmcnt(1)
	v_lshlrev_b32_e32 v54, 16, v42
	v_and_b32_e32 v55, 0xffff0000, v42
	v_lshlrev_b32_e32 v56, 16, v43
	v_and_b32_e32 v57, 0xffff0000, v43
	v_lshlrev_b32_e32 v58, 16, v44
	v_and_b32_e32 v59, 0xffff0000, v44
	v_lshlrev_b32_e32 v60, 16, v45
	v_and_b32_e32 v61, 0xffff0000, v45
	v_pk_mul_f32 v[88:89], v[80:81], v[54:55]
	v_pk_mul_f32 v[90:91], v[82:83], v[56:57]
	v_pk_mul_f32 v[92:93], v[84:85], v[58:59]
	v_pk_mul_f32 v[94:95], v[86:87], v[60:61]
	v_lshlrev_b32_e32 v54, 16, v46
	v_and_b32_e32 v55, 0xffff0000, v46
	v_lshlrev_b32_e32 v56, 16, v47
	v_and_b32_e32 v57, 0xffff0000, v47
	v_lshlrev_b32_e32 v58, 16, v48
	v_and_b32_e32 v59, 0xffff0000, v48
	v_lshlrev_b32_e32 v60, 16, v49
	v_and_b32_e32 v61, 0xffff0000, v49
	v_pk_fma_f32 v[2:3], v[88:89], v[54:55], v[2:3]
	v_pk_fma_f32 v[4:5], v[90:91], v[56:57], v[4:5]
	v_pk_fma_f32 v[6:7], v[92:93], v[58:59], v[6:7]
	v_pk_fma_f32 v[8:9], v[94:95], v[60:61], v[8:9]
	s_waitcnt vmcnt(0)
	v_lshlrev_b32_e32 v54, 16, v50
	v_and_b32_e32 v55, 0xffff0000, v50
	v_lshlrev_b32_e32 v56, 16, v51
	v_and_b32_e32 v57, 0xffff0000, v51
	v_lshlrev_b32_e32 v58, 16, v52
	v_and_b32_e32 v59, 0xffff0000, v52
	v_lshlrev_b32_e32 v60, 16, v53
	v_and_b32_e32 v61, 0xffff0000, v53
	v_pk_mul_f32 v[2:3], v[2:3], v[54:55]
	v_pk_mul_f32 v[4:5], v[4:5], v[56:57]
	v_pk_mul_f32 v[6:7], v[6:7], v[58:59]
	v_pk_mul_f32 v[8:9], v[8:9], v[60:61]
	v_cvt_pk_bf16_f32 v2, v2, v3
	v_cvt_pk_bf16_f32 v3, v4, v5
	v_cvt_pk_bf16_f32 v4, v6, v7
	v_cvt_pk_bf16_f32 v5, v8, v9
	global_store_dwordx4 v23, v[2:5], s[34:35]
	v_lshl_add_u64 v[10:11], v[10:11], 0, s[40:41]
	v_lshl_add_u64 v[12:13], v[12:13], 0, s[42:43]
	s_mov_b64 s[4:5], 0x1fffff
	v_cmp_lt_u64_e32 vcc, s[4:5], v[10:11]
	s_or_b64 s[44:45], vcc, s[44:45]
	s_andn2_b64 exec, exec, s[44:45]
	s_cbranch_execnz .LBB0_460

.LBB0_676:
	s_or_saveexec_b64 s[42:43], s[40:41]
	s_lshl_b32 s40, s46, 6
	v_mov_b32_e32 v8, 0
	v_mov_b32_e32 v9, 0
	s_waitcnt vmcnt(5)
	v_mov_b32_e32 v10, 0
	v_mov_b32_e32 v11, 0
	s_xor_b64 exec, exec, s[42:43]
	s_cbranch_execz .LBB0_673
	v_lshl_add_u64 v[12:13], v[0:1], 2, s[38:39]
	v_add_u32_e32 v0, s40, v5
	v_mad_i64_i32 v[8:9], s[46:47], v0, s18, v[12:13]
	global_load_dword v10, v[8:9], off nt
	v_add_u32_e32 v8, 8, v0
	v_mad_i64_i32 v[8:9], s[46:47], v8, s18, v[12:13]
	global_load_dword v11, v[8:9], off nt
	v_add_u32_e32 v8, 16, v0
	v_mad_i64_i32 v[8:9], s[46:47], v8, s18, v[12:13]
	global_load_dword v14, v[8:9], off nt
	v_add_u32_e32 v8, 24, v0
	v_mad_i64_i32 v[8:9], s[46:47], v8, s18, v[12:13]
	global_load_dword v8, v[8:9], off nt
	s_waitcnt vmcnt(3)
	ds_write_b32 v7, v10
	s_waitcnt vmcnt(2)
	ds_write_b32 v7, v11 offset:1056
	s_waitcnt vmcnt(1)
	ds_write_b32 v7, v14 offset:2112
	s_waitcnt vmcnt(0)
	ds_write_b32 v7, v8 offset:3168
	v_add_u32_e32 v8, 32, v0
	v_mad_i64_i32 v[8:9], s[46:47], v8, s18, v[12:13]
	global_load_dword v8, v[8:9], off nt
	v_add_u32_e32 v9, 40, v0
	v_mad_i64_i32 v[10:11], s[46:47], v9, s18, v[12:13]
	global_load_dword v9, v[10:11], off nt
	v_add_u32_e32 v10, 48, v0
	v_add_u32_e32 v0, 56, v0
	v_mad_i64_i32 v[10:11], s[46:47], v10, s18, v[12:13]
	v_mad_i64_i32 v[12:13], s[46:47], v0, s18, v[12:13]
	global_load_dword v10, v[10:11], off nt
	s_nop 0
	global_load_dword v11, v[12:13], off nt
	s_branch .LBB0_673

.LBB0_683:
	s_or_saveexec_b64 s[42:43], s[40:41]
	s_and_b32 s40, s46, 0xffffffc0
	v_mov_b32_e32 v5, 0
	v_mov_b32_e32 v9, 0
	s_waitcnt vmcnt(5)
	v_mov_b32_e32 v10, 0
	v_mov_b32_e32 v11, 0
	s_xor_b64 exec, exec, s[42:43]
	s_cbranch_execz .LBB0_680
	v_ashrrev_i32_e32 v5, 31, v4
	v_lshl_add_u64 v[4:5], v[4:5], 2, s[38:39]
	s_mov_b64 s[46:47], 0x40c0
	v_lshl_add_u64 v[12:13], v[4:5], 0, s[46:47]
	s_waitcnt vmcnt(4)
	v_add_u32_e32 v14, s40, v7
	v_mad_i64_i32 v[4:5], s[46:47], v14, s18, v[12:13]
	global_load_dword v9, v[4:5], off nt
	v_add_u32_e32 v4, 8, v14
	v_mad_i64_i32 v[4:5], s[46:47], v4, s18, v[12:13]
	global_load_dword v10, v[4:5], off nt
	v_add_u32_e32 v4, 16, v14
	v_mad_i64_i32 v[4:5], s[46:47], v4, s18, v[12:13]
	global_load_dword v11, v[4:5], off nt
	v_add_u32_e32 v4, 24, v14
	v_mad_i64_i32 v[4:5], s[46:47], v4, s18, v[12:13]
	global_load_dword v4, v[4:5], off nt
	s_waitcnt vmcnt(3)
	ds_write_b32 v0, v9
	s_waitcnt vmcnt(2)
	ds_write_b32 v0, v10 offset:1056
	s_waitcnt vmcnt(1)
	ds_write_b32 v0, v11 offset:2112
	s_waitcnt vmcnt(0)
	ds_write_b32 v0, v4 offset:3168
	v_add_u32_e32 v4, 32, v14
	v_mad_i64_i32 v[4:5], s[46:47], v4, s18, v[12:13]
	global_load_dword v5, v[4:5], off nt
	v_add_u32_e32 v4, 40, v14
	v_mad_i64_i32 v[10:11], s[46:47], v4, s18, v[12:13]
	v_add_u32_e32 v4, 48, v14
	global_load_dword v9, v[10:11], off nt
	v_mad_i64_i32 v[10:11], s[46:47], v4, s18, v[12:13]
	v_add_u32_e32 v4, 56, v14
	v_mad_i64_i32 v[12:13], s[46:47], v4, s18, v[12:13]
	global_load_dword v10, v[10:11], off nt
	s_nop 0
	global_load_dword v11, v[12:13], off nt
	s_branch .LBB0_680

.LBB0_690:
	s_lshl_b32 s42, s43, 6
	v_mov_b32_e32 v0, 0
	s_andn2_b64 vcc, exec, s[44:45]
	v_mov_b32_e32 v9, 0
	s_waitcnt vmcnt(5)
	v_mov_b32_e32 v10, 0
	v_mov_b32_e32 v11, 0
	s_cbranch_vccnz .LBB0_687
	s_lshl_b32 s43, s43, 10
	s_sub_i32 s46, 0, s43
	s_sub_i32 s43, s33, s43
	v_add_u32_e32 v12, s42, v5
	v_add_u32_e32 v0, s43, v4
	v_ashrrev_i32_e32 v13, 31, v12
	v_lshl_add_u64 v[10:11], v[0:1], 2, s[40:41]
	v_lshlrev_b64 v[12:13], 12, v[12:13]
	v_lshl_add_u64 v[12:13], v[10:11], 0, v[12:13]
	v_add_co_u32_e32 v10, vcc, 0x8000, v12
	global_load_dword v0, v[12:13], off nt
	s_nop 0
	v_addc_co_u32_e32 v11, vcc, 0, v13, vcc
	global_load_dword v9, v[10:11], off nt
	v_add_co_u32_e32 v10, vcc, s3, v12
	s_nop 1
	v_addc_co_u32_e32 v11, vcc, 0, v13, vcc
	global_load_dword v14, v[10:11], off nt
	v_add_co_u32_e32 v10, vcc, 0x18000, v12
	s_nop 1
	v_addc_co_u32_e32 v11, vcc, 0, v13, vcc
	global_load_dword v10, v[10:11], off nt
	s_waitcnt vmcnt(3)
	ds_write_b32 v7, v0
	s_waitcnt vmcnt(2)
	ds_write_b32 v7, v9 offset:1056
	s_waitcnt vmcnt(1)
	ds_write_b32 v7, v14 offset:2112
	s_waitcnt vmcnt(0)
	ds_write_b32 v7, v10 offset:3168
	v_add_co_u32_e32 v10, vcc, 0x20000, v12
	s_nop 1
	v_addc_co_u32_e32 v11, vcc, 0, v13, vcc
	global_load_dword v0, v[10:11], off nt
	v_add_co_u32_e32 v10, vcc, 0x28000, v12
	s_nop 1
	v_addc_co_u32_e32 v11, vcc, 0, v13, vcc
	global_load_dword v9, v[10:11], off nt
	v_add_co_u32_e32 v10, vcc, 0x30000, v12
	s_nop 1
	v_addc_co_u32_e32 v11, vcc, 0, v13, vcc
	v_add_co_u32_e32 v12, vcc, 0x38000, v12
	global_load_dword v10, v[10:11], off nt
	s_nop 0
	v_addc_co_u32_e32 v13, vcc, 0, v13, vcc
	global_load_dword v11, v[12:13], off nt
	s_branch .LBB0_687

.LBB0_697:
	s_lshl_b32 s38, s39, 6
	v_mov_b32_e32 v0, 0
	s_andn2_b64 vcc, exec, s[42:43]
	v_mov_b32_e32 v9, 0
	s_waitcnt vmcnt(5)
	v_mov_b32_e32 v10, 0
	v_mov_b32_e32 v11, 0
	s_cbranch_vccnz .LBB0_694
	s_lshl_b32 s39, s39, 10
	s_sub_i32 s44, 0, s39
	s_sub_i32 s39, s33, s39
	v_add_u32_e32 v12, s38, v5
	v_add_u32_e32 v0, s39, v4
	v_ashrrev_i32_e32 v13, 31, v12
	v_lshl_add_u64 v[10:11], v[0:1], 2, s[40:41]
	v_lshlrev_b64 v[12:13], 12, v[12:13]
	v_lshl_add_u64 v[12:13], v[10:11], 0, v[12:13]
	v_add_co_u32_e32 v10, vcc, 0x8000, v12
	global_load_dword v0, v[12:13], off nt
	s_nop 0
	v_addc_co_u32_e32 v11, vcc, 0, v13, vcc
	global_load_dword v9, v[10:11], off nt
	v_add_co_u32_e32 v10, vcc, s3, v12
	s_nop 1
	v_addc_co_u32_e32 v11, vcc, 0, v13, vcc
	global_load_dword v14, v[10:11], off nt
	v_add_co_u32_e32 v10, vcc, 0x18000, v12
	s_nop 1
	v_addc_co_u32_e32 v11, vcc, 0, v13, vcc
	global_load_dword v10, v[10:11], off nt
	s_waitcnt vmcnt(3)
	ds_write_b32 v7, v0
	s_waitcnt vmcnt(2)
	ds_write_b32 v7, v9 offset:1056
	s_waitcnt vmcnt(1)
	ds_write_b32 v7, v14 offset:2112
	s_waitcnt vmcnt(0)
	ds_write_b32 v7, v10 offset:3168
	v_add_co_u32_e32 v10, vcc, 0x20000, v12
	s_nop 1
	v_addc_co_u32_e32 v11, vcc, 0, v13, vcc
	global_load_dword v0, v[10:11], off nt
	v_add_co_u32_e32 v10, vcc, 0x28000, v12
	s_nop 1
	v_addc_co_u32_e32 v11, vcc, 0, v13, vcc
	global_load_dword v9, v[10:11], off nt
	v_add_co_u32_e32 v10, vcc, 0x30000, v12
	s_nop 1
	v_addc_co_u32_e32 v11, vcc, 0, v13, vcc
	v_add_co_u32_e32 v12, vcc, 0x38000, v12
	global_load_dword v10, v[10:11], off nt
	s_nop 0
	v_addc_co_u32_e32 v13, vcc, 0, v13, vcc
	global_load_dword v11, v[12:13], off nt
	s_branch .LBB0_694

.LBB0_704:
	s_or_saveexec_b64 s[42:43], s[40:41]
	s_lshl_b32 s40, s49, 6
	v_mov_b32_e32 v8, 0
	v_mov_b32_e32 v9, 0
	s_waitcnt vmcnt(5)
	v_mov_b32_e32 v10, 0
	v_mov_b32_e32 v11, 0
	s_xor_b64 exec, exec, s[42:43]
	s_cbranch_execz .LBB0_701
	v_lshl_add_u64 v[12:13], v[0:1], 2, s[38:39]
	v_add_u32_e32 v0, s40, v5
	v_mad_i64_i32 v[8:9], s[50:51], v0, s19, v[12:13]
	global_load_dword v10, v[8:9], off nt
	v_add_u32_e32 v8, 8, v0
	v_mad_i64_i32 v[8:9], s[50:51], v8, s19, v[12:13]
	global_load_dword v11, v[8:9], off nt
	v_add_u32_e32 v8, 16, v0
	v_mad_i64_i32 v[8:9], s[50:51], v8, s19, v[12:13]
	global_load_dword v14, v[8:9], off nt
	v_add_u32_e32 v8, 24, v0
	v_mad_i64_i32 v[8:9], s[50:51], v8, s19, v[12:13]
	global_load_dword v8, v[8:9], off nt
	s_waitcnt vmcnt(3)
	ds_write_b32 v7, v10
	s_waitcnt vmcnt(2)
	ds_write_b32 v7, v11 offset:1056
	s_waitcnt vmcnt(1)
	ds_write_b32 v7, v14 offset:2112
	s_waitcnt vmcnt(0)
	ds_write_b32 v7, v8 offset:3168
	v_add_u32_e32 v8, 32, v0
	v_mad_i64_i32 v[8:9], s[50:51], v8, s19, v[12:13]
	global_load_dword v8, v[8:9], off nt
	v_add_u32_e32 v9, 40, v0
	v_mad_i64_i32 v[10:11], s[50:51], v9, s19, v[12:13]
	global_load_dword v9, v[10:11], off nt
	v_add_u32_e32 v10, 48, v0
	v_add_u32_e32 v0, 56, v0
	v_mad_i64_i32 v[10:11], s[50:51], v10, s19, v[12:13]
	v_mad_i64_i32 v[12:13], s[50:51], v0, s19, v[12:13]
	global_load_dword v10, v[10:11], off nt
	s_nop 0
	global_load_dword v11, v[12:13], off nt
	s_branch .LBB0_701

.LBB0_711:
	s_lshl_b32 s40, s41, 6
	v_mov_b32_e32 v0, 0
	s_andn2_b64 vcc, exec, s[42:43]
	v_mov_b32_e32 v9, 0
	s_waitcnt vmcnt(5)
	v_mov_b32_e32 v10, 0
	v_mov_b32_e32 v11, 0
	s_cbranch_vccnz .LBB0_708
	s_lshl_b32 s41, s41, 10
	s_sub_i32 s44, 0, s41
	s_sub_i32 s41, s33, s41
	v_add_u32_e32 v12, s40, v5
	v_add_u32_e32 v0, s41, v4
	v_ashrrev_i32_e32 v13, 31, v12
	v_lshl_add_u64 v[10:11], v[0:1], 2, s[38:39]
	v_lshlrev_b64 v[12:13], 12, v[12:13]
	v_lshl_add_u64 v[12:13], v[10:11], 0, v[12:13]
	v_add_co_u32_e32 v10, vcc, 0x8000, v12
	global_load_dword v0, v[12:13], off nt
	s_nop 0
	v_addc_co_u32_e32 v11, vcc, 0, v13, vcc
	global_load_dword v9, v[10:11], off nt
	v_add_co_u32_e32 v10, vcc, s3, v12
	s_nop 1
	v_addc_co_u32_e32 v11, vcc, 0, v13, vcc
	global_load_dword v14, v[10:11], off nt
	v_add_co_u32_e32 v10, vcc, 0x18000, v12
	s_nop 1
	v_addc_co_u32_e32 v11, vcc, 0, v13, vcc
	global_load_dword v10, v[10:11], off nt
	s_waitcnt vmcnt(3)
	ds_write_b32 v7, v0
	s_waitcnt vmcnt(2)
	ds_write_b32 v7, v9 offset:1056
	s_waitcnt vmcnt(1)
	ds_write_b32 v7, v14 offset:2112
	s_waitcnt vmcnt(0)
	ds_write_b32 v7, v10 offset:3168
	v_add_co_u32_e32 v10, vcc, 0x20000, v12
	s_nop 1
	v_addc_co_u32_e32 v11, vcc, 0, v13, vcc
	global_load_dword v0, v[10:11], off nt
	v_add_co_u32_e32 v10, vcc, 0x28000, v12
	s_nop 1
	v_addc_co_u32_e32 v11, vcc, 0, v13, vcc
	global_load_dword v9, v[10:11], off nt
	v_add_co_u32_e32 v10, vcc, 0x30000, v12
	s_nop 1
	v_addc_co_u32_e32 v11, vcc, 0, v13, vcc
	v_add_co_u32_e32 v12, vcc, 0x38000, v12
	global_load_dword v10, v[10:11], off nt
	s_nop 0
	v_addc_co_u32_e32 v13, vcc, 0, v13, vcc
	global_load_dword v11, v[12:13], off nt
	s_branch .LBB0_708

.LBB0_718:
	s_lshl_b32 s42, s43, 6
	v_mov_b32_e32 v0, 0
	s_andn2_b64 vcc, exec, s[44:45]
	v_mov_b32_e32 v9, 0
	s_waitcnt vmcnt(5)
	v_mov_b32_e32 v10, 0
	v_mov_b32_e32 v11, 0
	s_cbranch_vccnz .LBB0_715
	s_lshl_b32 s43, s43, 7
	s_sub_i32 s46, 0, s43
	s_sub_i32 s43, s33, s43
	v_add_u32_e32 v12, s42, v5
	v_add_u32_e32 v0, s43, v4
	v_ashrrev_i32_e32 v13, 31, v12
	v_lshl_add_u64 v[10:11], v[0:1], 2, s[40:41]
	v_lshlrev_b64 v[12:13], 9, v[12:13]
	v_lshl_add_u64 v[12:13], v[10:11], 0, v[12:13]
	v_add_co_u32_e32 v10, vcc, 0x1000, v12
	global_load_dword v0, v[12:13], off nt
	s_nop 0
	v_addc_co_u32_e32 v11, vcc, 0, v13, vcc
	global_load_dword v9, v[10:11], off nt
	v_add_co_u32_e32 v10, vcc, 0x2000, v12
	s_nop 1
	v_addc_co_u32_e32 v11, vcc, 0, v13, vcc
	global_load_dword v14, v[10:11], off nt
	v_add_co_u32_e32 v10, vcc, 0x3000, v12
	s_nop 1
	v_addc_co_u32_e32 v11, vcc, 0, v13, vcc
	global_load_dword v10, v[10:11], off nt
	s_waitcnt vmcnt(3)
	ds_write_b32 v7, v0
	s_waitcnt vmcnt(2)
	ds_write_b32 v7, v9 offset:1056
	s_waitcnt vmcnt(1)
	ds_write_b32 v7, v14 offset:2112
	s_waitcnt vmcnt(0)
	ds_write_b32 v7, v10 offset:3168
	v_add_co_u32_e32 v10, vcc, s6, v12
	s_nop 1
	v_addc_co_u32_e32 v11, vcc, 0, v13, vcc
	global_load_dword v0, v[10:11], off nt
	v_add_co_u32_e32 v10, vcc, 0x5000, v12
	s_nop 1
	v_addc_co_u32_e32 v11, vcc, 0, v13, vcc
	global_load_dword v9, v[10:11], off nt
	v_add_co_u32_e32 v10, vcc, 0x6000, v12
	s_nop 1
	v_addc_co_u32_e32 v11, vcc, 0, v13, vcc
	v_add_co_u32_e32 v12, vcc, 0x7000, v12
	global_load_dword v10, v[10:11], off nt
	s_nop 0
	v_addc_co_u32_e32 v13, vcc, 0, v13, vcc
	global_load_dword v11, v[12:13], off nt
	s_branch .LBB0_715

.LBB0_725:
	v_mov_b32_e32 v0, 0
	s_andn2_b64 vcc, exec, s[46:47]
	v_mov_b32_e32 v9, 0
	s_waitcnt vmcnt(5)
	v_mov_b32_e32 v10, 0
	v_mov_b32_e32 v11, 0
	s_cbranch_vccnz .LBB0_722
	s_sub_i32 s45, s33, s44
	v_add_u32_e32 v12, s44, v5
	v_add_u32_e32 v0, s45, v4
	v_ashrrev_i32_e32 v13, 31, v12
	v_lshl_add_u64 v[10:11], v[0:1], 2, s[42:43]
	v_lshlrev_b64 v[12:13], 8, v[12:13]
	v_lshl_add_u64 v[10:11], v[10:11], 0, v[12:13]
	v_add_co_u32_e32 v12, vcc, 0x1000, v10
	s_sub_i32 s48, 0, s44
	s_nop 0
	v_addc_co_u32_e32 v13, vcc, 0, v11, vcc
	s_waitcnt vmcnt(4)
	v_add_co_u32_e32 v14, vcc, 0x2000, v10
	s_nop 1
	v_addc_co_u32_e32 v15, vcc, 0, v11, vcc
	v_add_co_u32_e32 v16, vcc, 0x3000, v10
	s_nop 1
	v_addc_co_u32_e32 v17, vcc, 0, v11, vcc
	global_load_dword v18, v[10:11], off nt
	global_load_dword v19, v[10:11], off offset:2048 nt
	global_load_dword v20, v[12:13], off nt
	s_nop 0
	global_load_dword v12, v[12:13], off offset:2048 nt
	s_nop 0
	global_load_dword v0, v[14:15], off nt
	global_load_dword v9, v[14:15], off offset:2048 nt
	global_load_dword v10, v[16:17], off nt
	global_load_dword v11, v[16:17], off offset:2048 nt
	s_waitcnt vmcnt(7)
	ds_write_b32 v7, v18
	s_waitcnt vmcnt(6)
	ds_write_b32 v7, v19 offset:1056
	s_waitcnt vmcnt(5)
	ds_write_b32 v7, v20 offset:2112
	s_waitcnt vmcnt(4)
	ds_write_b32 v7, v12 offset:3168
	s_branch .LBB0_722

.LBB0_732:
	s_lshl_b32 s42, s43, 6
	v_mov_b32_e32 v0, 0
	s_andn2_b64 vcc, exec, s[44:45]
	v_mov_b32_e32 v9, 0
	s_waitcnt vmcnt(5)
	v_mov_b32_e32 v10, 0
	v_mov_b32_e32 v11, 0
	s_cbranch_vccnz .LBB0_729
	s_lshl_b32 s43, s43, 7
	s_sub_i32 s46, 0, s43
	s_sub_i32 s43, s33, s43
	v_add_u32_e32 v12, s42, v5
	v_add_u32_e32 v0, s43, v4
	v_ashrrev_i32_e32 v13, 31, v12
	v_lshl_add_u64 v[10:11], v[0:1], 2, s[38:39]
	v_lshlrev_b64 v[12:13], 9, v[12:13]
	v_lshl_add_u64 v[12:13], v[10:11], 0, v[12:13]
	v_add_co_u32_e32 v10, vcc, 0x1000, v12
	global_load_dword v0, v[12:13], off nt
	s_nop 0
	v_addc_co_u32_e32 v11, vcc, 0, v13, vcc
	global_load_dword v9, v[10:11], off nt
	v_add_co_u32_e32 v10, vcc, 0x2000, v12
	s_nop 1
	v_addc_co_u32_e32 v11, vcc, 0, v13, vcc
	global_load_dword v14, v[10:11], off nt
	v_add_co_u32_e32 v10, vcc, 0x3000, v12
	s_nop 1
	v_addc_co_u32_e32 v11, vcc, 0, v13, vcc
	global_load_dword v10, v[10:11], off nt
	s_waitcnt vmcnt(3)
	ds_write_b32 v7, v0
	s_waitcnt vmcnt(2)
	ds_write_b32 v7, v9 offset:1056
	s_waitcnt vmcnt(1)
	ds_write_b32 v7, v14 offset:2112
	s_waitcnt vmcnt(0)
	ds_write_b32 v7, v10 offset:3168
	v_add_co_u32_e32 v10, vcc, s6, v12
	s_nop 1
	v_addc_co_u32_e32 v11, vcc, 0, v13, vcc
	global_load_dword v0, v[10:11], off nt
	v_add_co_u32_e32 v10, vcc, 0x5000, v12
	s_nop 1
	v_addc_co_u32_e32 v11, vcc, 0, v13, vcc
	global_load_dword v9, v[10:11], off nt
	v_add_co_u32_e32 v10, vcc, 0x6000, v12
	s_nop 1
	v_addc_co_u32_e32 v11, vcc, 0, v13, vcc
	v_add_co_u32_e32 v12, vcc, 0x7000, v12
	global_load_dword v10, v[10:11], off nt
	s_nop 0
	v_addc_co_u32_e32 v13, vcc, 0, v13, vcc
	global_load_dword v11, v[12:13], off nt
	s_branch .LBB0_729

.LBB0_739:
	v_mov_b32_e32 v0, 0
	s_andn2_b64 vcc, exec, s[42:43]
	v_mov_b32_e32 v9, 0
	s_waitcnt vmcnt(5)
	v_mov_b32_e32 v10, 0
	v_mov_b32_e32 v11, 0
	s_cbranch_vccnz .LBB0_736
	s_sub_i32 s36, s33, s40
	v_add_u32_e32 v12, s40, v5
	v_add_u32_e32 v0, s36, v4
	v_ashrrev_i32_e32 v13, 31, v12
	v_lshl_add_u64 v[10:11], v[0:1], 2, s[38:39]
	v_lshlrev_b64 v[12:13], 8, v[12:13]
	v_lshl_add_u64 v[10:11], v[10:11], 0, v[12:13]
	v_add_co_u32_e32 v12, vcc, 0x1000, v10
	s_sub_i32 s36, 0, s40
	s_nop 0
	v_addc_co_u32_e32 v13, vcc, 0, v11, vcc
	s_waitcnt vmcnt(4)
	v_add_co_u32_e32 v14, vcc, 0x2000, v10
	s_nop 1
	v_addc_co_u32_e32 v15, vcc, 0, v11, vcc
	v_add_co_u32_e32 v16, vcc, 0x3000, v10
	s_nop 1
	v_addc_co_u32_e32 v17, vcc, 0, v11, vcc
	global_load_dword v18, v[10:11], off nt
	global_load_dword v19, v[10:11], off offset:2048 nt
	global_load_dword v20, v[12:13], off nt
	s_nop 0
	global_load_dword v12, v[12:13], off offset:2048 nt
	s_nop 0
	global_load_dword v0, v[14:15], off nt
	global_load_dword v9, v[14:15], off offset:2048 nt
	global_load_dword v10, v[16:17], off nt
	global_load_dword v11, v[16:17], off offset:2048 nt
	s_waitcnt vmcnt(7)
	ds_write_b32 v7, v18
	s_waitcnt vmcnt(6)
	ds_write_b32 v7, v19 offset:1056
	s_waitcnt vmcnt(5)
	ds_write_b32 v7, v20 offset:2112
	s_waitcnt vmcnt(4)
	ds_write_b32 v7, v12 offset:3168
	s_branch .LBB0_736
